# forget_logits K loop: all 32 loads of an iteration issued up front, MFMAs behind counted vmcnt waits (was 4 loads then vmcnt(0))
# baseline (speedup 1.0000x reference)
; __device__ __forceinline__ void forget_logits(KArgs A, int G) {
;     ...
;         for (int s = 0; s < 32; s += 2) {
;             const bf16x8 a0 = *(const bf16x8*)(ap + 32 * s), b0 = *(const bf16x8*)(bp + 32 * s), a1 = *(const bf16x8*)(ap + 32 * s + 32), b1 = *(const bf16x8*)(bp + 32 * s + 32);
;             acc0 = __builtin_amdgcn_mfma_f32_16x16x32_bf16(b0, a0, acc0, 0, 0, 0); acc1 = __builtin_amdgcn_mfma_f32_16x16x32_bf16(b1, a1, acc1, 0, 0, 0); }
;         const f32x4 acc = acc0 + acc1; const float rr = 1.0f / sqrtf(sq * (1.0f / 1024.0f) + EPS);
;         f32x4 o;
; #pragma unroll
;         for (int i = 0; i < 4; ++i) { const float x = acc[i] * rr + fb[i]; o[i] = LOG2E * (fminf(x, 0.f) - log1pf(expf(-fabsf(x)))); }
;         *(f32x4*)(logf + (size_t)row * 16 + 4 * fq) = o;
.LBB0_205:
	v_lshl_add_u64 v[24:25], v[20:21], 0, v[0:1]
	v_add_co_u32_e32 v24, vcc, 0x10000000, v24
	v_lshl_add_u64 v[26:27], v[22:23], 0, v[0:1]
	s_nop 0
	v_addc_co_u32_e32 v25, vcc, 0, v25, vcc
	v_add_co_u32_e32 v26, vcc, 0x1400000, v26
	global_load_dwordx4 v[46:49], v[24:25], off
	s_nop 0
	v_addc_co_u32_e32 v27, vcc, 0, v27, vcc
	global_load_dwordx4 v[110:113], v[26:27], off
	global_load_dwordx4 v[50:53], v[24:25], off offset:64
	global_load_dwordx4 v[114:117], v[26:27], off offset:64
	global_load_dwordx4 v[54:57], v[24:25], off offset:128
	global_load_dwordx4 v[118:121], v[26:27], off offset:128
	global_load_dwordx4 v[58:61], v[24:25], off offset:192
	global_load_dwordx4 v[122:125], v[26:27], off offset:192
	global_load_dwordx4 v[62:65], v[24:25], off offset:256
	global_load_dwordx4 v[126:129], v[26:27], off offset:256
	global_load_dwordx4 v[66:69], v[24:25], off offset:320
	global_load_dwordx4 v[130:133], v[26:27], off offset:320
	global_load_dwordx4 v[70:73], v[24:25], off offset:384
	global_load_dwordx4 v[134:137], v[26:27], off offset:384
	global_load_dwordx4 v[74:77], v[24:25], off offset:448
	global_load_dwordx4 v[138:141], v[26:27], off offset:448
	global_load_dwordx4 v[78:81], v[24:25], off offset:512
	global_load_dwordx4 v[142:145], v[26:27], off offset:512
	global_load_dwordx4 v[82:85], v[24:25], off offset:576
	global_load_dwordx4 v[146:149], v[26:27], off offset:576
	global_load_dwordx4 v[86:89], v[24:25], off offset:640
	global_load_dwordx4 v[150:153], v[26:27], off offset:640
	global_load_dwordx4 v[90:93], v[24:25], off offset:704
	global_load_dwordx4 v[154:157], v[26:27], off offset:704
	global_load_dwordx4 v[94:97], v[24:25], off offset:768
	global_load_dwordx4 v[158:161], v[26:27], off offset:768
	global_load_dwordx4 v[98:101], v[24:25], off offset:832
	global_load_dwordx4 v[162:165], v[26:27], off offset:832
	global_load_dwordx4 v[102:105], v[24:25], off offset:896
	global_load_dwordx4 v[166:169], v[26:27], off offset:896
	global_load_dwordx4 v[106:109], v[24:25], off offset:960
	global_load_dwordx4 v[170:173], v[26:27], off offset:960
	s_add_i32 s7, s7, 16
	v_lshl_add_u64 v[22:23], v[22:23], 0, s[16:17]
	v_lshl_add_u64 v[20:21], v[20:21], 0, s[16:17]
	s_cmp_gt_u32 s7, 29
	s_waitcnt vmcnt(30)
	v_mfma_f32_16x16x32_bf16 v[6:9], v[110:113], v[46:49], v[6:9]
	s_waitcnt vmcnt(28)
	v_mfma_f32_16x16x32_bf16 v[10:13], v[114:117], v[50:53], v[10:13]
	s_waitcnt vmcnt(26)
	v_mfma_f32_16x16x32_bf16 v[6:9], v[118:121], v[54:57], v[6:9]
	s_waitcnt vmcnt(24)
	v_mfma_f32_16x16x32_bf16 v[10:13], v[122:125], v[58:61], v[10:13]
	s_waitcnt vmcnt(22)
	v_mfma_f32_16x16x32_bf16 v[6:9], v[126:129], v[62:65], v[6:9]
	s_waitcnt vmcnt(20)
	v_mfma_f32_16x16x32_bf16 v[10:13], v[130:133], v[66:69], v[10:13]
	s_waitcnt vmcnt(18)
	v_mfma_f32_16x16x32_bf16 v[6:9], v[134:137], v[70:73], v[6:9]
	s_waitcnt vmcnt(16)
	v_mfma_f32_16x16x32_bf16 v[10:13], v[138:141], v[74:77], v[10:13]
	s_waitcnt vmcnt(14)
	v_mfma_f32_16x16x32_bf16 v[6:9], v[142:145], v[78:81], v[6:9]
	s_waitcnt vmcnt(12)
	v_mfma_f32_16x16x32_bf16 v[10:13], v[146:149], v[82:85], v[10:13]
	s_waitcnt vmcnt(10)
	v_mfma_f32_16x16x32_bf16 v[6:9], v[150:153], v[86:89], v[6:9]
	s_waitcnt vmcnt(8)
	v_mfma_f32_16x16x32_bf16 v[10:13], v[154:157], v[90:93], v[10:13]
	s_waitcnt vmcnt(6)
	v_mfma_f32_16x16x32_bf16 v[6:9], v[158:161], v[94:97], v[6:9]
	s_waitcnt vmcnt(4)
	v_mfma_f32_16x16x32_bf16 v[10:13], v[162:165], v[98:101], v[10:13]
	s_waitcnt vmcnt(2)
	v_mfma_f32_16x16x32_bf16 v[6:9], v[166:169], v[102:105], v[6:9]
	s_waitcnt vmcnt(0)
	v_mfma_f32_16x16x32_bf16 v[10:13], v[170:173], v[106:109], v[10:13]
	s_cbranch_scc0 .LBB0_205
	v_fmamk_f32 v20, v29, 0x3a800000, v232
	s_mov_b32 s7, 0xf800000
	v_mul_f32_e32 v21, 0x4f800000, v20
	v_cmp_gt_f32_e32 vcc, s7, v20
	s_nop 2
	v_pk_add_f32 v[10:11], v[6:7], v[10:11]
	s_mov_b32 s7, 0xb2a5705f
	v_cndmask_b32_e32 v20, v20, v21, vcc
	v_sqrt_f32_e32 v21, v20
	s_mov_b32 s18, 0xc2b17218
	s_mov_b32 s20, 0x3f2aaaab
	s_mov_b32 s38, 0x3e9b6dac
	v_add_u32_e32 v22, -1, v21
	v_fma_f32 v24, -v22, v21, v20
	v_add_u32_e32 v23, 1, v21
	v_cmp_ge_f32_e64 s[42:43], 0, v24
	s_mov_b32 s44, 0x3f317218
	s_mov_b32 s46, 0xb102e308
	v_cndmask_b32_e64 v22, v21, v22, s[42:43]
	v_fma_f32 v21, -v23, v21, v20
	v_cmp_lt_f32_e64 s[42:43], 0, v21
	s_mov_b32 s21, 0x33800000
	s_add_i32 s6, s6, s89
	v_cndmask_b32_e64 v21, v22, v23, s[42:43]
	v_mul_f32_e32 v22, 0x37800000, v21
	v_cndmask_b32_e32 v21, v21, v22, vcc
	v_mov_b32_e32 v22, 0x260
	v_cmp_class_f32_e32 vcc, v20, v22
	s_mov_b32 s42, 0x3f2aaada
	s_add_i32 s5, s5, s4
	v_cndmask_b32_e32 v20, v21, v20, vcc
	v_div_scale_f32 v21, s[10:11], v20, v20, 1.0
	v_rcp_f32_e32 v22, v21
	s_mov_b32 s11, 0x42ce8ed0
	s_mov_b32 s10, 0x3ecc95a3
	s_cmpk_gt_i32 s6, 0xff
	v_fma_f32 v6, -v21, v22, 1.0
	v_fmac_f32_e32 v22, v6, v22
	v_div_scale_f32 v6, vcc, 1.0, v20, 1.0
	v_mul_f32_e32 v7, v6, v22
	v_fma_f32 v23, -v21, v7, v6
	v_fmac_f32_e32 v7, v23, v22
	v_fma_f32 v6, -v21, v7, v6
	v_div_fmas_f32 v6, v6, v22, v7
	v_div_fixup_f32 v29, v6, v20, 1.0
	v_fma_f32 v10, v29, v10, v2
	v_mul_f32_e64 v6, |v10|, s19
	v_fma_f32 v7, |v10|, s19, -v6
	v_rndne_f32_e32 v20, v6
	v_fma_f32 v7, |v10|, s7, v7
	v_sub_f32_e32 v6, v6, v20
	v_add_f32_e32 v6, v6, v7
	v_exp_f32_e32 v21, v6
	v_cvt_i32_f32_e32 v20, v20
	v_pk_add_f32 v[6:7], v[8:9], v[12:13]
	v_cmp_ngt_f32_e64 vcc, |v10|, s11
	v_min_f32_e32 v8, 0, v10
	v_ldexp_f32 v9, v21, v20
	v_cndmask_b32_e32 v9, 0, v9, vcc
	v_cmp_nlt_f32_e64 vcc, |v10|, s18
	v_fma_f32 v21, v29, v11, v3
	s_nop 0
	v_cndmask_b32_e32 v48, v243, v9, vcc
	v_add_f32_e32 v12, 1.0, v48
	v_add_f32_e32 v9, -1.0, v12
	v_sub_f32_e32 v10, v9, v12
	v_add_f32_e32 v10, 1.0, v10
; __device__ __forceinline__ void forget_logits(KArgs A, int G) {
;     ...
;         const f32x4 acc = acc0 + acc1; const float rr = 1.0f / sqrtf(sq * (1.0f / 1024.0f) + EPS);
;         f32x4 o;
; #pragma unroll
;         for (int i = 0; i < 4; ++i) { const float x = acc[i] * rr + fb[i]; o[i] = LOG2E * (fminf(x, 0.f) - log1pf(expf(-fabsf(x)))); }
	v_sub_f32_e32 v9, v48, v9
	v_add_f32_e32 v13, v9, v10
	v_mul_f32_e64 v9, |v21|, s19
	v_fma_f32 v10, |v21|, s19, -v9
	v_rndne_f32_e32 v11, v9
	v_fma_f32 v10, |v21|, s7, v10
	v_sub_f32_e32 v9, v9, v11
	v_add_f32_e32 v9, v9, v10
	v_exp_f32_e32 v22, v9
	v_cvt_i32_f32_e32 v23, v11
	v_cvt_f64_f32_e32 v[10:11], v12
	v_frexp_exp_i32_f64_e32 v24, v[10:11]
	v_cmp_ngt_f32_e64 vcc, |v21|, s11
	v_ldexp_f32 v10, v22, v23
	v_min_f32_e32 v9, 0, v21
	v_cndmask_b32_e32 v10, 0, v10, vcc
	v_cmp_nlt_f32_e64 vcc, |v21|, s18
	v_frexp_mant_f32_e32 v20, v12
	s_nop 0
	v_cndmask_b32_e32 v49, v243, v10, vcc
	v_add_f32_e32 v21, 1.0, v49
	v_add_f32_e32 v10, -1.0, v21
	v_sub_f32_e32 v11, v10, v21
	v_add_f32_e32 v11, 1.0, v11
	v_sub_f32_e32 v10, v49, v10
	v_add_f32_e32 v22, v10, v11
	v_frexp_mant_f32_e32 v23, v21
	v_cvt_f64_f32_e32 v[10:11], v21
	v_frexp_exp_i32_f64_e32 v10, v[10:11]
	v_cmp_gt_f32_e32 vcc, s20, v23
	s_nop 1
	v_subbrev_co_u32_e32 v38, vcc, 0, v10, vcc
	v_cmp_gt_f32_e32 vcc, s20, v20
	s_nop 1
	v_subbrev_co_u32_e32 v39, vcc, 0, v24, vcc
	v_sub_u32_e32 v11, 0, v39
	v_ldexp_f32 v10, v12, v11
	v_ldexp_f32 v12, v13, v11
	v_sub_u32_e32 v13, 0, v38
	v_ldexp_f32 v11, v21, v13
	v_pk_add_f32 v[20:21], v[10:11], 1.0 op_sel_hi:[1,0]
	v_ldexp_f32 v13, v22, v13
	v_pk_add_f32 v[22:23], v[20:21], -1.0 op_sel_hi:[1,0]
	v_pk_add_f32 v[30:31], v[10:11], -1.0 op_sel_hi:[1,0]
	v_pk_add_f32 v[22:23], v[10:11], v[22:23] neg_lo:[0,1] neg_hi:[0,1]
	v_pk_add_f32 v[32:33], v[30:31], 1.0 op_sel_hi:[1,0]
	v_pk_add_f32 v[22:23], v[12:13], v[22:23]
	v_pk_add_f32 v[10:11], v[10:11], v[32:33] neg_lo:[0,1] neg_hi:[0,1]
	v_pk_add_f32 v[24:25], v[20:21], v[22:23]
	v_pk_add_f32 v[10:11], v[12:13], v[10:11]
	v_rcp_f32_e32 v26, v24
	v_rcp_f32_e32 v27, v25
	v_pk_add_f32 v[12:13], v[30:31], v[10:11]
	v_pk_add_f32 v[20:21], v[20:21], v[24:25] neg_lo:[0,1] neg_hi:[0,1]
	v_pk_add_f32 v[30:31], v[30:31], v[12:13] neg_lo:[0,1] neg_hi:[0,1]
	v_pk_add_f32 v[20:21], v[22:23], v[20:21]
	v_pk_mul_f32 v[22:23], v[12:13], v[26:27]
	v_pk_add_f32 v[10:11], v[10:11], v[30:31]
	v_pk_mul_f32 v[30:31], v[24:25], v[22:23]
	s_nop 0
	v_pk_fma_f32 v[32:33], v[22:23], v[24:25], v[30:31] neg_lo:[0,0,1] neg_hi:[0,0,1]
	s_nop 0
	v_pk_fma_f32 v[32:33], v[22:23], v[20:21], v[32:33]
	s_nop 0
	v_pk_add_f32 v[34:35], v[30:31], v[32:33]
	s_nop 0
	v_pk_add_f32 v[36:37], v[12:13], v[34:35] neg_lo:[0,1] neg_hi:[0,1]
	v_pk_add_f32 v[30:31], v[34:35], v[30:31] neg_lo:[0,1] neg_hi:[0,1]
	v_pk_add_f32 v[12:13], v[12:13], v[36:37] neg_lo:[0,1] neg_hi:[0,1]
	s_nop 0
	v_pk_add_f32 v[12:13], v[12:13], v[34:35] neg_lo:[0,1] neg_hi:[0,1]
	s_nop 0
	v_pk_add_f32 v[10:11], v[10:11], v[12:13]
	v_pk_add_f32 v[12:13], v[30:31], v[32:33] neg_lo:[0,1] neg_hi:[0,1]
	s_nop 0
	v_pk_add_f32 v[10:11], v[12:13], v[10:11]
	s_nop 0
	v_pk_add_f32 v[12:13], v[36:37], v[10:11]
	s_nop 0
	v_pk_mul_f32 v[30:31], v[26:27], v[12:13]
	s_nop 0
	v_pk_mul_f32 v[32:33], v[24:25], v[30:31]
	s_nop 0
	v_pk_fma_f32 v[24:25], v[30:31], v[24:25], v[32:33] neg_lo:[0,0,1] neg_hi:[0,0,1]
	s_nop 0
	v_pk_fma_f32 v[20:21], v[30:31], v[20:21], v[24:25]
	v_pk_add_f32 v[24:25], v[36:37], v[12:13] neg_lo:[0,1] neg_hi:[0,1]
	s_nop 0
	v_pk_add_f32 v[10:11], v[10:11], v[24:25]
	v_pk_add_f32 v[24:25], v[32:33], v[20:21]
	s_nop 0
	v_pk_add_f32 v[34:35], v[12:13], v[24:25] neg_lo:[0,1] neg_hi:[0,1]
	v_pk_add_f32 v[32:33], v[24:25], v[32:33] neg_lo:[0,1] neg_hi:[0,1]
	v_pk_add_f32 v[12:13], v[12:13], v[34:35] neg_lo:[0,1] neg_hi:[0,1]
	s_nop 0
	v_pk_add_f32 v[12:13], v[12:13], v[24:25] neg_lo:[0,1] neg_hi:[0,1]
	v_cvt_f32_i32_e32 v25, v38
	v_pk_add_f32 v[10:11], v[10:11], v[12:13]
	v_pk_add_f32 v[12:13], v[32:33], v[20:21] neg_lo:[0,1] neg_hi:[0,1]
	v_cvt_f32_i32_e32 v24, v39
	v_pk_add_f32 v[10:11], v[12:13], v[10:11]
	v_pk_add_f32 v[12:13], v[22:23], v[30:31]
	v_pk_add_f32 v[10:11], v[34:35], v[10:11]
	v_pk_add_f32 v[20:21], v[12:13], v[22:23] neg_lo:[0,1] neg_hi:[0,1]
	v_pk_mul_f32 v[10:11], v[26:27], v[10:11]
	v_pk_add_f32 v[20:21], v[30:31], v[20:21] neg_lo:[0,1] neg_hi:[0,1]
	v_mov_b64_e32 v[26:27], s[10:11]
	v_pk_add_f32 v[10:11], v[20:21], v[10:11]
	v_pk_mul_f32 v[32:33], v[24:25], s[44:45] op_sel_hi:[1,0]
	v_pk_add_f32 v[20:21], v[12:13], v[10:11]
	v_pk_fma_f32 v[34:35], v[24:25], s[44:45], v[32:33] op_sel_hi:[1,0,1] neg_lo:[0,0,1] neg_hi:[0,0,1]
	v_pk_mul_f32 v[22:23], v[20:21], v[20:21]
	v_pk_add_f32 v[12:13], v[20:21], v[12:13] neg_lo:[0,1] neg_hi:[0,1]
	v_pk_fma_f32 v[30:31], v[22:23], s[38:39], v[26:27] op_sel_hi:[1,0,0]
	v_pk_add_f32 v[10:11], v[10:11], v[12:13] neg_lo:[0,1] neg_hi:[0,1]
	v_ldexp_f32 v12, v20, 1
	v_pk_fma_f32 v[30:31], v[22:23], v[30:31], s[42:43] op_sel_hi:[1,1,0]
	v_ldexp_f32 v13, v21, 1
	v_pk_mul_f32 v[20:21], v[20:21], v[22:23]
	v_ldexp_f32 v37, v11, 1
	v_pk_mul_f32 v[20:21], v[20:21], v[30:31]
	v_ldexp_f32 v10, v10, 1
	v_pk_add_f32 v[22:23], v[12:13], v[20:21]
	v_mov_b32_e32 v11, v37
	v_pk_add_f32 v[12:13], v[22:23], v[12:13] neg_lo:[0,1] neg_hi:[0,1]
	v_pk_fma_f32 v[24:25], v[24:25], s[46:47], v[34:35] op_sel_hi:[1,0,1]
	v_pk_add_f32 v[12:13], v[20:21], v[12:13] neg_lo:[0,1] neg_hi:[0,1]
	v_pk_add_f32 v[34:35], v[32:33], v[24:25]
	v_pk_add_f32 v[30:31], v[10:11], v[12:13]
	v_mov_b32_e32 v21, v13
	v_mov_b32_e32 v11, v31
	v_mov_b32_e32 v13, v23
	v_mov_b32_e32 v20, v32
	v_mov_b32_e32 v36, v24
	v_pk_add_f32 v[10:11], v[10:11], v[12:13]
	v_pk_add_f32 v[12:13], v[22:23], v[30:31]
	v_pk_add_f32 v[20:21], v[20:21], v[36:37]
	v_mov_b32_e32 v36, v34
	v_mov_b32_e32 v37, v33
	v_mov_b32_e32 v38, v12
	v_mov_b32_e32 v39, v25
	v_mov_b32_e32 v42, v34
	v_mov_b32_e32 v43, v23
	v_mov_b32_e32 v44, v12
	v_mov_b32_e32 v45, v31
	v_pk_add_f32 v[40:41], v[36:37], v[38:39]
; __device__ __forceinline__ void forget_logits(KArgs A, int G) {
;     ...
;         const f32x4 acc = acc0 + acc1; const float rr = 1.0f / sqrtf(sq * (1.0f / 1024.0f) + EPS);
;         f32x4 o;
; #pragma unroll
;         for (int i = 0; i < 4; ++i) { const float x = acc[i] * rr + fb[i]; o[i] = LOG2E * (fminf(x, 0.f) - log1pf(expf(-fabsf(x)))); }
	v_pk_add_f32 v[42:43], v[42:43], v[44:45]
	v_pk_add_f32 v[44:45], v[34:35], v[12:13]
	v_pk_add_f32 v[36:37], v[40:41], v[36:37] neg_lo:[0,1] neg_hi:[0,1]
	v_mov_b32_e32 v40, v12
	v_mov_b32_e32 v41, v45
	v_mov_b32_e32 v46, v22
	v_mov_b32_e32 v47, v35
	v_pk_add_f32 v[40:41], v[40:41], v[46:47] neg_lo:[0,1] neg_hi:[0,1]
	v_mov_b32_e32 v46, v34
	v_mov_b32_e32 v47, v45
	v_mov_b32_e32 v33, v41
	v_pk_add_f32 v[32:33], v[46:47], v[32:33] neg_lo:[0,1] neg_hi:[0,1]
	v_pk_add_f32 v[38:39], v[38:39], v[36:37] neg_lo:[0,1] neg_hi:[0,1]
	v_mov_b32_e32 v46, v32
	v_mov_b32_e32 v47, v37
	v_mov_b32_e32 v37, v23
	v_pk_add_f32 v[46:47], v[24:25], v[46:47] neg_lo:[0,1] neg_hi:[0,1]
	v_pk_add_f32 v[36:37], v[42:43], v[36:37] neg_lo:[0,1] neg_hi:[0,1]
	v_mov_b32_e32 v25, v35
	v_pk_add_f32 v[12:13], v[12:13], v[22:23] neg_lo:[0,1] neg_hi:[0,1]
	v_pk_add_f32 v[20:21], v[20:21], v[36:37] neg_lo:[0,1] neg_hi:[0,1]
	v_pk_add_f32 v[22:23], v[24:25], v[32:33] neg_lo:[0,1] neg_hi:[0,1]
	v_pk_add_f32 v[10:11], v[10:11], v[40:41] neg_lo:[0,1] neg_hi:[0,1]
	v_pk_add_f32 v[12:13], v[30:31], v[12:13] neg_lo:[0,1] neg_hi:[0,1]
	v_pk_add_f32 v[24:25], v[10:11], v[22:23]
	v_mov_b32_e32 v11, v21
	v_pk_add_f32 v[30:31], v[38:39], v[20:21]
	v_pk_add_f32 v[10:11], v[46:47], v[10:11]
	v_mov_b32_e32 v23, v39
	v_pk_add_f32 v[10:11], v[10:11], v[22:23] neg_lo:[0,1] neg_hi:[0,1]
	v_mov_b32_e32 v20, v24
	v_mov_b32_e32 v21, v31
	v_pk_add_f32 v[20:21], v[20:21], v[10:11] neg_lo:[0,1] neg_hi:[0,1]
	v_pk_add_f32 v[10:11], v[12:13], v[10:11] neg_lo:[0,1] neg_hi:[0,1]
	v_pk_add_f32 v[20:21], v[22:23], v[20:21] neg_lo:[0,1] neg_hi:[0,1]
	v_pk_add_f32 v[12:13], v[30:31], v[24:25]
	v_pk_add_f32 v[10:11], v[10:11], v[20:21]
	v_pk_add_f32 v[20:21], v[44:45], v[12:13]
	s_mov_b32 s10, 0x7f800000
	v_pk_add_f32 v[22:23], v[20:21], v[44:45] neg_lo:[0,1] neg_hi:[0,1]
	v_cmp_neq_f32_e32 vcc, s10, v48
	v_pk_add_f32 v[12:13], v[12:13], v[22:23] neg_lo:[0,1] neg_hi:[0,1]
	s_nop 0
	v_pk_add_f32 v[10:11], v[10:11], v[12:13]
	v_fma_f32 v12, v29, v6, v4
	v_mul_f32_e64 v6, |v12|, s19
	v_pk_add_f32 v[10:11], v[20:21], v[10:11]
	v_fma_f32 v13, |v12|, s19, -v6
	v_rndne_f32_e32 v20, v6
	v_fma_f32 v13, |v12|, s7, v13
	v_sub_f32_e32 v6, v6, v20
	v_add_f32_e32 v6, v6, v13
	v_cndmask_b32_e32 v10, v243, v10, vcc
	v_cmp_neq_f32_e32 vcc, s10, v49
	v_exp_f32_e32 v13, v6
	v_cvt_i32_f32_e32 v20, v20
	v_cndmask_b32_e32 v11, v243, v11, vcc
	v_cmp_lt_f32_e64 vcc, |v49|, s21
	v_min_f32_e32 v6, 0, v12
	v_fma_f32 v21, v29, v7, v5
	v_cndmask_b32_e32 v11, v11, v49, vcc
	v_cmp_lt_f32_e64 vcc, |v48|, s21
	v_mul_f32_e64 v7, |v21|, s19
	s_nop 0
	v_cndmask_b32_e32 v10, v10, v48, vcc
	v_pk_add_f32 v[10:11], v[8:9], v[10:11] neg_lo:[0,1] neg_hi:[0,1]
	v_ldexp_f32 v8, v13, v20
	v_cmp_ngt_f32_e64 vcc, |v12|, s11
	s_nop 1
	v_cndmask_b32_e32 v8, 0, v8, vcc
	v_cmp_nlt_f32_e64 vcc, |v12|, s18
	s_nop 1
	v_cndmask_b32_e32 v46, v243, v8, vcc
	v_add_f32_e32 v12, 1.0, v46
	v_add_f32_e32 v8, -1.0, v12
	v_sub_f32_e32 v9, v8, v12
	v_add_f32_e32 v9, 1.0, v9
	v_sub_f32_e32 v8, v46, v8
	v_add_f32_e32 v13, v8, v9
	v_fma_f32 v8, |v21|, s19, -v7
	v_rndne_f32_e32 v9, v7
	v_fma_f32 v8, |v21|, s7, v8
	v_sub_f32_e32 v7, v7, v9
	v_add_f32_e32 v7, v7, v8
	v_exp_f32_e32 v22, v7
	v_cvt_i32_f32_e32 v23, v9
	v_cvt_f64_f32_e32 v[8:9], v12
	v_frexp_exp_i32_f64_e32 v24, v[8:9]
	v_cmp_ngt_f32_e64 vcc, |v21|, s11
	v_ldexp_f32 v8, v22, v23
	v_min_f32_e32 v7, 0, v21
	v_cndmask_b32_e32 v8, 0, v8, vcc
	v_cmp_nlt_f32_e64 vcc, |v21|, s18
	v_frexp_mant_f32_e32 v20, v12
	s_nop 0
	v_cndmask_b32_e32 v29, v243, v8, vcc
	v_add_f32_e32 v21, 1.0, v29
	v_add_f32_e32 v8, -1.0, v21
	v_sub_f32_e32 v9, v8, v21
	v_add_f32_e32 v9, 1.0, v9
	v_sub_f32_e32 v8, v29, v8
	v_add_f32_e32 v22, v8, v9
	v_frexp_mant_f32_e32 v23, v21
	v_cvt_f64_f32_e32 v[8:9], v21
	v_frexp_exp_i32_f64_e32 v8, v[8:9]
	v_cmp_gt_f32_e32 vcc, s20, v23
	s_nop 1
	v_subbrev_co_u32_e32 v40, vcc, 0, v8, vcc
	v_cmp_gt_f32_e32 vcc, s20, v20
	s_nop 1
	v_subbrev_co_u32_e32 v41, vcc, 0, v24, vcc
	v_sub_u32_e32 v9, 0, v41
	v_ldexp_f32 v8, v12, v9
	v_ldexp_f32 v12, v13, v9
	v_sub_u32_e32 v13, 0, v40
	v_ldexp_f32 v9, v21, v13
	v_pk_add_f32 v[20:21], v[8:9], 1.0 op_sel_hi:[1,0]
	v_ldexp_f32 v13, v22, v13
	v_pk_add_f32 v[22:23], v[20:21], -1.0 op_sel_hi:[1,0]
	v_pk_add_f32 v[32:33], v[8:9], -1.0 op_sel_hi:[1,0]
	v_pk_add_f32 v[22:23], v[8:9], v[22:23] neg_lo:[0,1] neg_hi:[0,1]
	v_pk_add_f32 v[34:35], v[32:33], 1.0 op_sel_hi:[1,0]
	v_pk_add_f32 v[22:23], v[12:13], v[22:23]
	v_pk_add_f32 v[8:9], v[8:9], v[34:35] neg_lo:[0,1] neg_hi:[0,1]
	v_pk_add_f32 v[24:25], v[20:21], v[22:23]
	v_pk_add_f32 v[8:9], v[12:13], v[8:9]
	v_rcp_f32_e32 v30, v24
	v_rcp_f32_e32 v31, v25
	v_pk_add_f32 v[12:13], v[32:33], v[8:9]
	v_pk_add_f32 v[20:21], v[20:21], v[24:25] neg_lo:[0,1] neg_hi:[0,1]
	v_pk_add_f32 v[32:33], v[32:33], v[12:13] neg_lo:[0,1] neg_hi:[0,1]
	v_pk_add_f32 v[20:21], v[22:23], v[20:21]
	v_pk_mul_f32 v[22:23], v[12:13], v[30:31]
	v_pk_add_f32 v[8:9], v[8:9], v[32:33]
	v_pk_mul_f32 v[32:33], v[24:25], v[22:23]
	v_cmp_neq_f32_e32 vcc, s10, v46
	v_pk_fma_f32 v[34:35], v[22:23], v[24:25], v[32:33] neg_lo:[0,0,1] neg_hi:[0,0,1]
	s_nop 0
	v_pk_fma_f32 v[34:35], v[22:23], v[20:21], v[34:35]
	s_nop 0
	v_pk_add_f32 v[36:37], v[32:33], v[34:35]
	s_nop 0
	v_pk_add_f32 v[38:39], v[12:13], v[36:37] neg_lo:[0,1] neg_hi:[0,1]
	v_pk_add_f32 v[32:33], v[36:37], v[32:33] neg_lo:[0,1] neg_hi:[0,1]
	v_pk_add_f32 v[12:13], v[12:13], v[38:39] neg_lo:[0,1] neg_hi:[0,1]
	s_nop 0
	v_pk_add_f32 v[12:13], v[12:13], v[36:37] neg_lo:[0,1] neg_hi:[0,1]
	s_nop 0
	v_pk_add_f32 v[8:9], v[8:9], v[12:13]
; __device__ __forceinline__ void forget_logits(KArgs A, int G) {
;     ...
;         const f32x4 acc = acc0 + acc1; const float rr = 1.0f / sqrtf(sq * (1.0f / 1024.0f) + EPS);
;         f32x4 o;
; #pragma unroll
;         for (int i = 0; i < 4; ++i) { const float x = acc[i] * rr + fb[i]; o[i] = LOG2E * (fminf(x, 0.f) - log1pf(expf(-fabsf(x)))); }
;         *(f32x4*)(logf + (size_t)row * 16 + 4 * fq) = o;
	v_pk_add_f32 v[12:13], v[32:33], v[34:35] neg_lo:[0,1] neg_hi:[0,1]
	s_nop 0
	v_pk_add_f32 v[8:9], v[12:13], v[8:9]
	s_nop 0
	v_pk_add_f32 v[12:13], v[38:39], v[8:9]
	s_nop 0
	v_pk_mul_f32 v[32:33], v[30:31], v[12:13]
	s_nop 0
	v_pk_mul_f32 v[34:35], v[24:25], v[32:33]
	s_nop 0
	v_pk_fma_f32 v[24:25], v[32:33], v[24:25], v[34:35] neg_lo:[0,0,1] neg_hi:[0,0,1]
	s_nop 0
	v_pk_fma_f32 v[20:21], v[32:33], v[20:21], v[24:25]
	v_pk_add_f32 v[24:25], v[38:39], v[12:13] neg_lo:[0,1] neg_hi:[0,1]
	s_nop 0
	v_pk_add_f32 v[8:9], v[8:9], v[24:25]
	v_pk_add_f32 v[24:25], v[34:35], v[20:21]
	s_nop 0
	v_pk_add_f32 v[36:37], v[12:13], v[24:25] neg_lo:[0,1] neg_hi:[0,1]
	v_pk_add_f32 v[34:35], v[24:25], v[34:35] neg_lo:[0,1] neg_hi:[0,1]
	v_pk_add_f32 v[12:13], v[12:13], v[36:37] neg_lo:[0,1] neg_hi:[0,1]
	s_nop 0
	v_pk_add_f32 v[12:13], v[12:13], v[24:25] neg_lo:[0,1] neg_hi:[0,1]
	s_nop 0
	v_pk_add_f32 v[8:9], v[8:9], v[12:13]
	v_pk_add_f32 v[12:13], v[34:35], v[20:21] neg_lo:[0,1] neg_hi:[0,1]
	s_nop 0
	v_pk_add_f32 v[8:9], v[12:13], v[8:9]
	v_pk_add_f32 v[12:13], v[22:23], v[32:33]
	v_pk_add_f32 v[8:9], v[36:37], v[8:9]
	v_pk_add_f32 v[20:21], v[12:13], v[22:23] neg_lo:[0,1] neg_hi:[0,1]
	v_pk_mul_f32 v[8:9], v[30:31], v[8:9]
	v_pk_add_f32 v[20:21], v[32:33], v[20:21] neg_lo:[0,1] neg_hi:[0,1]
	v_cvt_f32_i32_e32 v23, v40
	v_pk_add_f32 v[8:9], v[20:21], v[8:9]
	v_cvt_f32_i32_e32 v22, v41
	v_pk_add_f32 v[20:21], v[12:13], v[8:9]
	v_pk_mul_f32 v[30:31], v[22:23], s[44:45] op_sel_hi:[1,0]
	v_pk_mul_f32 v[24:25], v[20:21], v[20:21]
	v_pk_add_f32 v[12:13], v[20:21], v[12:13] neg_lo:[0,1] neg_hi:[0,1]
	v_pk_fma_f32 v[26:27], v[24:25], s[38:39], v[26:27] op_sel_hi:[1,0,0]
	v_pk_add_f32 v[8:9], v[8:9], v[12:13] neg_lo:[0,1] neg_hi:[0,1]
	v_ldexp_f32 v12, v20, 1
	v_pk_fma_f32 v[26:27], v[24:25], v[26:27], s[42:43] op_sel_hi:[1,1,0]
	v_ldexp_f32 v13, v21, 1
	v_pk_mul_f32 v[20:21], v[20:21], v[24:25]
	v_ldexp_f32 v35, v9, 1
	v_pk_mul_f32 v[20:21], v[20:21], v[26:27]
	v_ldexp_f32 v8, v8, 1
	v_pk_add_f32 v[24:25], v[12:13], v[20:21]
	v_mov_b32_e32 v9, v35
	v_pk_add_f32 v[12:13], v[24:25], v[12:13] neg_lo:[0,1] neg_hi:[0,1]
	v_pk_fma_f32 v[32:33], v[22:23], s[44:45], v[30:31] op_sel_hi:[1,0,1] neg_lo:[0,0,1] neg_hi:[0,0,1]
	v_pk_add_f32 v[12:13], v[20:21], v[12:13] neg_lo:[0,1] neg_hi:[0,1]
	v_pk_fma_f32 v[22:23], v[22:23], s[46:47], v[32:33] op_sel_hi:[1,0,1]
	v_pk_add_f32 v[26:27], v[8:9], v[12:13]
	v_mov_b32_e32 v21, v13
	v_mov_b32_e32 v9, v27
	v_mov_b32_e32 v13, v25
	v_pk_add_f32 v[32:33], v[30:31], v[22:23]
	v_mov_b32_e32 v20, v30
	v_mov_b32_e32 v34, v22
	v_pk_add_f32 v[8:9], v[8:9], v[12:13]
	v_pk_add_f32 v[12:13], v[24:25], v[26:27]
	v_pk_add_f32 v[20:21], v[20:21], v[34:35]
	v_mov_b32_e32 v34, v32
	v_mov_b32_e32 v35, v31
	v_mov_b32_e32 v36, v12
	v_mov_b32_e32 v37, v23
	v_mov_b32_e32 v40, v32
	v_mov_b32_e32 v41, v25
	v_mov_b32_e32 v42, v12
	v_mov_b32_e32 v43, v27
	v_pk_add_f32 v[38:39], v[34:35], v[36:37]
	v_pk_add_f32 v[40:41], v[40:41], v[42:43]
	v_pk_add_f32 v[42:43], v[32:33], v[12:13]
	v_pk_add_f32 v[34:35], v[38:39], v[34:35] neg_lo:[0,1] neg_hi:[0,1]
	v_mov_b32_e32 v38, v12
	v_mov_b32_e32 v39, v43
	v_mov_b32_e32 v44, v24
	v_mov_b32_e32 v45, v33
	v_pk_add_f32 v[38:39], v[38:39], v[44:45] neg_lo:[0,1] neg_hi:[0,1]
	v_mov_b32_e32 v44, v32
	v_mov_b32_e32 v45, v43
	v_mov_b32_e32 v31, v39
	v_pk_add_f32 v[30:31], v[44:45], v[30:31] neg_lo:[0,1] neg_hi:[0,1]
	v_pk_add_f32 v[36:37], v[36:37], v[34:35] neg_lo:[0,1] neg_hi:[0,1]
	v_mov_b32_e32 v44, v30
	v_mov_b32_e32 v45, v35
	v_mov_b32_e32 v35, v25
	v_pk_add_f32 v[44:45], v[22:23], v[44:45] neg_lo:[0,1] neg_hi:[0,1]
	v_pk_add_f32 v[34:35], v[40:41], v[34:35] neg_lo:[0,1] neg_hi:[0,1]
	v_mov_b32_e32 v23, v33
	v_pk_add_f32 v[20:21], v[20:21], v[34:35] neg_lo:[0,1] neg_hi:[0,1]
	v_pk_add_f32 v[22:23], v[22:23], v[30:31] neg_lo:[0,1] neg_hi:[0,1]
	v_pk_add_f32 v[8:9], v[8:9], v[38:39] neg_lo:[0,1] neg_hi:[0,1]
	v_pk_add_f32 v[12:13], v[12:13], v[24:25] neg_lo:[0,1] neg_hi:[0,1]
	v_pk_add_f32 v[24:25], v[8:9], v[22:23]
	v_mov_b32_e32 v9, v21
	v_pk_add_f32 v[12:13], v[26:27], v[12:13] neg_lo:[0,1] neg_hi:[0,1]
	v_pk_add_f32 v[26:27], v[36:37], v[20:21]
	v_pk_add_f32 v[8:9], v[44:45], v[8:9]
	v_mov_b32_e32 v23, v37
	v_pk_add_f32 v[8:9], v[8:9], v[22:23] neg_lo:[0,1] neg_hi:[0,1]
	v_mov_b32_e32 v20, v24
	v_mov_b32_e32 v21, v27
	v_pk_add_f32 v[20:21], v[20:21], v[8:9] neg_lo:[0,1] neg_hi:[0,1]
	v_pk_add_f32 v[8:9], v[12:13], v[8:9] neg_lo:[0,1] neg_hi:[0,1]
	v_pk_add_f32 v[20:21], v[22:23], v[20:21] neg_lo:[0,1] neg_hi:[0,1]
	v_pk_add_f32 v[12:13], v[26:27], v[24:25]
	v_pk_add_f32 v[8:9], v[8:9], v[20:21]
	v_pk_add_f32 v[20:21], v[42:43], v[12:13]
	s_nop 0
	v_pk_add_f32 v[22:23], v[20:21], v[42:43] neg_lo:[0,1] neg_hi:[0,1]
	s_nop 0
	v_pk_add_f32 v[12:13], v[12:13], v[22:23] neg_lo:[0,1] neg_hi:[0,1]
	s_nop 0
	v_pk_add_f32 v[8:9], v[8:9], v[12:13]
	s_nop 0
	v_pk_add_f32 v[8:9], v[20:21], v[8:9]
	s_nop 0
	v_cndmask_b32_e32 v8, v243, v8, vcc
	v_cmp_neq_f32_e32 vcc, s10, v29
	s_mov_b32 s10, 0x3fb8aa3b
	s_nop 0
	v_cndmask_b32_e32 v9, v243, v9, vcc
	v_cmp_lt_f32_e64 vcc, |v29|, s21
	s_nop 1
	v_cndmask_b32_e32 v9, v9, v29, vcc
	v_cmp_lt_f32_e64 vcc, |v46|, s21
	s_nop 1
	v_cndmask_b32_e32 v8, v8, v46, vcc
	v_pk_add_f32 v[6:7], v[6:7], v[8:9] neg_lo:[0,1] neg_hi:[0,1]
	s_nop 0
	v_pk_mul_f32 v[8:9], v[6:7], s[10:11] op_sel_hi:[1,0]
	v_pk_mul_f32 v[6:7], v[10:11], s[10:11] op_sel_hi:[1,0]
	v_lshlrev_b64 v[10:11], 6, v[18:19]
	v_lshl_add_u64 v[10:11], v[14:15], 0, v[10:11]
	global_store_dwordx4 v[10:11], v[6:9], off
	s_cbranch_scc0 .LBB0_204
